# previous best plus: RG-LRU gate sigmoids as two reciprocals instead of one reciprocal of the product and three multiplies (22 of 32 element sites), matching exponent clamps dropped where traced
# speedup vs baseline: 1.0026x; 1.0026x over previous
; #define LAS __attribute__((address_space(3)))
; template <bool PASSB>
; __device__ __forceinline__ void lru_unit(LAS unsigned char* lds, const Params& p, int b, int hd, int chunk) {
;     ...
;         for (int tb = 0; tb < 4; ++tb) {
;             f32x4 ar = (f32x4){0.f, 0.f, 0.f, 0.f}, ai = (f32x4){0.f, 0.f, 0.f, 0.f};
; #pragma unroll
;             for (int ks = 0; ks < 4; ++ks) {
;                 const bf16x8 a = *(const LAS bf16x8*)(XCB + (tb * 16 + fr) * 272 + (ks * 32 + fq * 8) * 2);
;                 ar = __builtin_amdgcn_mfma_f32_16x16x32_bf16(a, wf[0][ks], ar, 0, 0, 0);
;                 ai = __builtin_amdgcn_mfma_f32_16x16x32_bf16(a, wf[1][ks], ai, 0, 0, 0);
;             }
; #pragma unroll
;             for (int j = 0; j < 4; ++j) {
;                 const int token = fq * 16 + tb * 4 + j;
;                 const float xcv = XCF[token * 132 + chl];
;                 const float e1 = __expf(fminf(-(ar[j] + brv), 40.f)), e2 = __expf(fminf(-(ai[j] + biv), 40.f));
;                 const float inv = __builtin_amdgcn_rcpf((1.0f + e1) * (1.0f + e2));
;                 const float r = inv * (1.0f + e2), ig = inv * (1.0f + e1);
;                 const float a = __expf(clv * r);
;                 const float bb = __builtin_amdgcn_sqrtf(fmaxf(1.0f - a * a, 0.f)) * (ig * xcv);
;                 hrun = a * hrun + bb; prun *= a;
;                 if (PASSB) { hl[tb * 4 + j] = hrun; pl[tb * 4 + j] = prun; }
;             }
.LBB0_493:
	v_add3_u32 v132, s28, v110, v127
	ds_read_b128 v[134:137], v132
	ds_read_b128 v[138:141], v132 offset:64
	ds_read_b128 v[146:149], v132 offset:128
	v_lshl_add_u32 v131, v124, 2, s28
	v_lshlrev_b32_e32 v104, 2, v125
	s_waitcnt lgkmcnt(2)
	v_mfma_f32_16x16x32_bf16 v[142:145], v[134:137], v[24:27], 0
	v_add3_u32 v131, v131, v104, v126
	v_add_u32_e32 v133, 0x4400, v131
	ds_read2_b32 v[150:151], v133 offset1:132
	v_mfma_f32_16x16x32_bf16 v[134:137], v[134:137], v[28:31], 0
	s_add_i32 s0, s0, 64
	s_add_i32 s11, s11, 1
	s_cmpk_eq_i32 s0, 0x3c0
	s_waitcnt lgkmcnt(2)
	v_mfma_f32_16x16x32_bf16 v[142:145], v[138:141], v[16:19], v[142:145]
	v_mfma_f32_16x16x32_bf16 v[134:137], v[138:141], v[20:23], v[134:137]
	ds_read_b128 v[138:141], v132 offset:192
	s_waitcnt lgkmcnt(2)
	v_mfma_f32_16x16x32_bf16 v[142:145], v[146:149], v[8:11], v[142:145]
	v_mfma_f32_16x16x32_bf16 v[134:137], v[146:149], v[12:15], v[134:137]
	s_waitcnt lgkmcnt(0)
	v_mfma_f32_16x16x32_bf16 v[142:145], v[138:141], v[0:3], v[142:145]
	v_mfma_f32_16x16x32_bf16 v[134:137], v[138:141], v[4:7], v[134:137]
	s_nop 6
	v_fma_f32 v133, v142, s72, v200
	v_fma_f32 v134, v134, s72, v201
	v_fma_f32 v138, v143, s72, v200
	v_fma_f32 v135, v135, s72, v201
	v_exp_f32_e32 v133, v133
	v_exp_f32_e32 v134, v134
	v_min_f32_e32 v138, s73, v138
	v_min_f32_e32 v135, s73, v135
	v_exp_f32_e32 v138, v138
	v_exp_f32_e32 v135, v135
	v_add_f32_e32 v133, 1.0, v133
	v_add_f32_e32 v134, 1.0, v134
	v_rcp_f32_e32 v139, v133
	v_add_f32_e32 v138, 1.0, v138
	v_add_f32_e32 v135, 1.0, v135
	v_mul_f32_e32 v140, v138, v135
	v_rcp_f32_e32 v140, v140
	v_rcp_f32_e32 v133, v134
	v_mul_f32_e32 v134, v202, v139
	v_mul_f32_e32 v135, v135, v140
	v_mul_f32_e32 v138, v138, v140
	v_fma_f32 v140, v144, s72, v200
	v_fma_f32 v136, v136, s72, v201
	v_exp_f32_e32 v134, v134
	v_min_f32_e32 v140, s73, v140
	v_exp_f32_e32 v140, v140
	v_exp_f32_e32 v136, v136
	v_fma_f32 v139, -v134, v134, 1.0 clamp
	v_sqrt_f32_e32 v139, v139
	v_mul_f32_e32 v135, v202, v135
	v_add_f32_e32 v142, 1.0, v140
	v_add_f32_e32 v136, 1.0, v136
	v_exp_f32_e32 v135, v135
	v_mul_f32_e32 v133, v150, v133
	v_mul_f32_e32 v133, v133, v139
	v_fmac_f32_e32 v133, 0, v134
	v_fma_f32 v139, -v135, v135, 1.0 clamp
	v_mul_f32_e32 v133, v135, v133
	v_mul_f32_e32 v152, v134, v135
	v_rcp_f32_e32 v135, v142
	s_nop 0
	v_mul_f32_e32 v135, v202, v135
	v_sqrt_f32_e32 v139, v139
	v_exp_f32_e32 v153, v135
	v_mul_f32_e32 v138, v151, v138
	v_add_u32_e32 v134, 0x4800, v131
	v_fmac_f32_e32 v133, v138, v139
	ds_read2_b32 v[150:151], v134 offset0:8 offset1:140
	ds_read_b128 v[138:141], v132 offset:4352
	v_fma_f32 v134, -v153, v153, 1.0 clamp
	v_sqrt_f32_e32 v155, v134
	v_fma_f32 v134, v145, s72, v200
	v_min_f32_e32 v134, s73, v134
	v_rcp_f32_e32 v154, v136
	ds_read_b128 v[142:145], v132 offset:4416
	v_exp_f32_e32 v156, v134
	v_fma_f32 v134, v137, s72, v201
	v_min_f32_e32 v157, s73, v134
	s_waitcnt lgkmcnt(1)
	v_mfma_f32_16x16x32_bf16 v[146:149], v[138:141], v[24:27], 0
	v_mul_f32_e32 v150, v150, v154
	v_add_f32_e32 v154, 1.0, v156
	v_mul_f32_e32 v133, v153, v133
	v_mfma_f32_16x16x32_bf16 v[134:137], v[138:141], v[28:31], 0
	v_exp_f32_e32 v157, v157
	ds_read_b128 v[138:141], v132 offset:4480
	s_waitcnt lgkmcnt(1)
	v_mfma_f32_16x16x32_bf16 v[146:149], v[142:145], v[16:19], v[146:149]
	v_fmac_f32_e32 v133, v150, v155
	v_add_f32_e32 v156, 1.0, v157
	v_mfma_f32_16x16x32_bf16 v[134:137], v[142:145], v[20:23], v[134:137]
	ds_read_b128 v[142:145], v132 offset:4544
	s_waitcnt lgkmcnt(1)
	v_mfma_f32_16x16x32_bf16 v[146:149], v[138:141], v[8:11], v[146:149]
	v_rcp_f32_e32 v150, v154
	v_mfma_f32_16x16x32_bf16 v[134:137], v[138:141], v[12:15], v[134:137]
	v_mul_f32_e32 v138, v202, v150
	v_exp_f32_e32 v150, v138
	s_waitcnt lgkmcnt(0)
	v_mfma_f32_16x16x32_bf16 v[138:141], v[142:145], v[0:3], v[146:149]
	v_mul_f32_e32 v133, v150, v133
	v_mfma_f32_16x16x32_bf16 v[134:137], v[142:145], v[4:7], v[134:137]
	s_nop 0
	v_fma_f32 v148, -v150, v150, 1.0 clamp
	s_nop 3
	v_fma_f32 v138, v138, s72, v200
	v_exp_f32_e32 v138, v138
	v_fma_f32 v134, v134, s72, v201
	v_exp_f32_e32 v134, v134
	v_add_f32_e32 v138, 1.0, v138
	v_fma_f32 v139, v139, s72, v200
	v_fma_f32 v135, v135, s72, v201
	v_add_f32_e32 v134, 1.0, v134
	v_rcp_f32_e32 v144, v138
	v_min_f32_e32 v139, s73, v139
	v_min_f32_e32 v135, s73, v135
	v_exp_f32_e32 v139, v139
	v_exp_f32_e32 v135, v135
	v_rcp_f32_e32 v138, v134
	v_mul_f32_e32 v134, v202, v144
	v_rcp_f32_e32 v147, v156
	v_sqrt_f32_e32 v142, v148
	v_add_f32_e32 v139, 1.0, v139
	v_add_f32_e32 v135, 1.0, v135
	v_mul_f32_e32 v143, v151, v147
	v_exp_f32_e32 v134, v134
	v_mul_f32_e32 v147, v139, v135
	v_rcp_f32_e32 v147, v147
	v_mul_f32_e32 v146, v153, v152
	v_fmac_f32_e32 v133, v143, v142
	v_add_u32_e32 v142, 0x4c00, v131
	v_mul_f32_e32 v145, v150, v146
	ds_read2_b32 v[142:143], v142 offset0:16 offset1:148
	v_fma_f32 v146, -v134, v134, 1.0 clamp
	v_mul_f32_e32 v135, v135, v147
	v_fma_f32 v140, v140, s72, v200
	v_fma_f32 v136, v136, s72, v201
	v_sqrt_f32_e32 v146, v146
	v_mul_f32_e32 v135, v202, v135
	v_min_f32_e32 v140, s73, v140
	v_exp_f32_e32 v135, v135
	v_exp_f32_e32 v140, v140
	v_exp_f32_e32 v136, v136
	s_waitcnt lgkmcnt(0)
	v_mul_f32_e32 v138, v142, v138
	v_mul_f32_e32 v138, v138, v146
	v_fmac_f32_e32 v138, v133, v134
	v_mul_f32_e32 v152, v135, v138
	v_add_f32_e32 v138, 1.0, v140
	v_add_f32_e32 v136, 1.0, v136
	v_mul_f32_e32 v133, v145, v134
	v_mul_f32_e32 v134, v139, v147
	v_fma_f32 v139, -v135, v135, 1.0 clamp
	v_mul_f32_e32 v133, v135, v133
	v_rcp_f32_e32 v135, v138
	s_nop 0
	v_mul_f32_e32 v135, v202, v135
	v_sqrt_f32_e32 v139, v139
	v_exp_f32_e32 v153, v135
	v_mul_f32_e32 v134, v143, v134
	v_fmac_f32_e32 v152, v134, v139
	v_add_u32_e32 v134, 0x5000, v131
	ds_read2_b32 v[150:151], v134 offset0:24 offset1:156
	ds_read_b128 v[142:145], v132 offset:8704
	v_fma_f32 v134, -v153, v153, 1.0 clamp
	v_sqrt_f32_e32 v155, v134
	v_fma_f32 v134, v141, s72, v200
	v_min_f32_e32 v134, s73, v134
	v_rcp_f32_e32 v154, v136
	ds_read_b128 v[138:141], v132 offset:8768
	v_exp_f32_e32 v156, v134
	v_fma_f32 v134, v137, s72, v201
	v_min_f32_e32 v157, s73, v134
	s_waitcnt lgkmcnt(1)
; #define LAS __attribute__((address_space(3)))
; template <bool PASSB>
; __device__ __forceinline__ void lru_unit(LAS unsigned char* lds, const Params& p, int b, int hd, int chunk) {
;     ...
;         for (int tb = 0; tb < 4; ++tb) {
;             f32x4 ar = (f32x4){0.f, 0.f, 0.f, 0.f}, ai = (f32x4){0.f, 0.f, 0.f, 0.f};
; #pragma unroll
;             for (int ks = 0; ks < 4; ++ks) {
;                 const bf16x8 a = *(const LAS bf16x8*)(XCB + (tb * 16 + fr) * 272 + (ks * 32 + fq * 8) * 2);
;                 ar = __builtin_amdgcn_mfma_f32_16x16x32_bf16(a, wf[0][ks], ar, 0, 0, 0);
;                 ai = __builtin_amdgcn_mfma_f32_16x16x32_bf16(a, wf[1][ks], ai, 0, 0, 0);
;             }
; #pragma unroll
;             for (int j = 0; j < 4; ++j) {
;                 const int token = fq * 16 + tb * 4 + j;
;                 const float xcv = XCF[token * 132 + chl];
;                 const float e1 = __expf(fminf(-(ar[j] + brv), 40.f)), e2 = __expf(fminf(-(ai[j] + biv), 40.f));
;                 const float inv = __builtin_amdgcn_rcpf((1.0f + e1) * (1.0f + e2));
;                 const float r = inv * (1.0f + e2), ig = inv * (1.0f + e1);
;                 const float a = __expf(clv * r);
;                 const float bb = __builtin_amdgcn_sqrtf(fmaxf(1.0f - a * a, 0.f)) * (ig * xcv);
;                 hrun = a * hrun + bb; prun *= a;
;                 if (PASSB) { hl[tb * 4 + j] = hrun; pl[tb * 4 + j] = prun; }
;             }
	v_mfma_f32_16x16x32_bf16 v[146:149], v[142:145], v[24:27], 0
	v_mul_f32_e32 v150, v150, v154
	v_add_f32_e32 v154, 1.0, v156
	v_mul_f32_e32 v152, v153, v152
	v_mfma_f32_16x16x32_bf16 v[134:137], v[142:145], v[28:31], 0
	v_exp_f32_e32 v157, v157
	ds_read_b128 v[142:145], v132 offset:8832
	s_waitcnt lgkmcnt(1)
	v_mfma_f32_16x16x32_bf16 v[146:149], v[138:141], v[16:19], v[146:149]
	v_fmac_f32_e32 v152, v150, v155
	v_add_f32_e32 v156, 1.0, v157
	v_mul_f32_e32 v133, v153, v133
	v_mfma_f32_16x16x32_bf16 v[134:137], v[138:141], v[20:23], v[134:137]
	ds_read_b128 v[138:141], v132 offset:8896
	s_waitcnt lgkmcnt(1)
	v_mfma_f32_16x16x32_bf16 v[146:149], v[142:145], v[8:11], v[146:149]
	v_rcp_f32_e32 v150, v154
	v_mfma_f32_16x16x32_bf16 v[134:137], v[142:145], v[12:15], v[134:137]
	v_mul_f32_e32 v142, v202, v150
	v_exp_f32_e32 v150, v142
	s_waitcnt lgkmcnt(0)
	v_mfma_f32_16x16x32_bf16 v[142:145], v[138:141], v[0:3], v[146:149]
	v_mul_f32_e32 v133, v150, v133
	v_mfma_f32_16x16x32_bf16 v[134:137], v[138:141], v[4:7], v[134:137]
	s_nop 0
	v_fma_f32 v147, -v150, v150, 1.0 clamp
	s_nop 3
	v_fma_f32 v138, v142, s72, v200
	v_min_f32_e32 v138, s73, v138
	v_exp_f32_e32 v138, v138
	v_fma_f32 v134, v134, s72, v201
	v_exp_f32_e32 v134, v134
	v_add_f32_e32 v140, 1.0, v138
	v_fma_f32 v143, v143, s72, v200
	v_add_f32_e32 v134, 1.0, v134
	v_rcp_f32_e32 v141, v140
	v_fma_f32 v135, v135, s72, v201
	v_sqrt_f32_e32 v139, v147
	v_min_f32_e32 v143, s73, v143
	v_rcp_f32_e32 v140, v134
	v_mul_f32_e32 v134, v202, v141
	v_min_f32_e32 v135, s73, v135
	v_exp_f32_e32 v134, v134
	v_rcp_f32_e32 v146, v156
	v_exp_f32_e32 v143, v143
	v_exp_f32_e32 v135, v135
	v_mul_f32_e32 v138, v151, v146
	v_mul_f32_e32 v142, v150, v152
	v_fmac_f32_e32 v142, v138, v139
	v_add_u32_e32 v138, 0x5400, v131
	ds_read2_b32 v[138:139], v138 offset0:32 offset1:164
	v_fma_f32 v146, -v134, v134, 1.0 clamp
	v_add_f32_e32 v143, 1.0, v143
	v_add_f32_e32 v135, 1.0, v135
	v_fma_f32 v141, v144, s72, v200
	v_fma_f32 v136, v136, s72, v201
	v_sqrt_f32_e32 v146, v146
	v_mul_f32_e32 v147, v143, v135
	v_min_f32_e32 v141, s73, v141
	v_rcp_f32_e32 v147, v147
	v_exp_f32_e32 v141, v141
	v_exp_f32_e32 v136, v136
	s_waitcnt lgkmcnt(0)
	v_mul_f32_e32 v138, v138, v140
	v_mul_f32_e32 v138, v138, v146
	v_mul_f32_e32 v135, v135, v147
	v_fmac_f32_e32 v138, v142, v134
	v_mul_f32_e32 v133, v133, v134
	v_mul_f32_e32 v134, v143, v147
	v_mul_f32_e32 v135, v202, v135
	v_mul_f32_e32 v134, v139, v134
	v_add_f32_e32 v139, 1.0, v141
	v_add_f32_e32 v136, 1.0, v136
	v_exp_f32_e32 v135, v135
	s_nop 0
	v_mul_f32_e32 v153, v135, v133
	v_rcp_f32_e32 v133, v139
	v_fma_f32 v140, -v135, v135, 1.0 clamp
	v_mul_f32_e32 v133, v202, v133
	v_sqrt_f32_e32 v140, v140
	v_exp_f32_e32 v154, v133
	v_mul_f32_e32 v152, v135, v138
	v_add_u32_e32 v133, 0x5800, v131
	v_fmac_f32_e32 v152, v134, v140
	v_fma_f32 v134, -v154, v154, 1.0 clamp
	v_sqrt_f32_e32 v155, v134
	v_fma_f32 v134, v145, s72, v200
	ds_read2_b32 v[150:151], v133 offset0:40 offset1:172
	v_rcp_f32_e32 v133, v136
	ds_read_b128 v[138:141], v132 offset:13056
	v_min_f32_e32 v134, s73, v134
	v_exp_f32_e32 v146, v134
	v_fma_f32 v134, v137, s72, v201
	v_min_f32_e32 v147, s73, v134
	ds_read_b128 v[134:137], v132 offset:13120
	v_exp_f32_e32 v147, v147
	s_waitcnt lgkmcnt(1)
	v_mfma_f32_16x16x32_bf16 v[142:145], v[138:141], v[24:27], 0
	v_mul_f32_e32 v133, v150, v133
	v_add_f32_e32 v150, 1.0, v146
	v_add_f32_e32 v156, 1.0, v147
	v_mfma_f32_16x16x32_bf16 v[138:141], v[138:141], v[28:31], 0
	ds_read_b128 v[146:149], v132 offset:13184
	s_waitcnt lgkmcnt(1)
	v_mfma_f32_16x16x32_bf16 v[142:145], v[134:137], v[16:19], v[142:145]
	v_mul_f32_e32 v152, v154, v152
	v_fmac_f32_e32 v152, v133, v155
	v_rcp_f32_e32 v133, v150
	v_mfma_f32_16x16x32_bf16 v[134:137], v[134:137], v[20:23], v[138:141]
	s_nop 2
	ds_read_b128 v[138:141], v132 offset:13248
	v_mul_f32_e32 v132, v202, v133
	s_waitcnt lgkmcnt(1)
; #define LAS __attribute__((address_space(3)))
; template <bool PASSB>
; __device__ __forceinline__ void lru_unit(LAS unsigned char* lds, const Params& p, int b, int hd, int chunk) {
;     ...
;         for (int tb = 0; tb < 4; ++tb) {
;             f32x4 ar = (f32x4){0.f, 0.f, 0.f, 0.f}, ai = (f32x4){0.f, 0.f, 0.f, 0.f};
; #pragma unroll
;             for (int ks = 0; ks < 4; ++ks) {
;                 const bf16x8 a = *(const LAS bf16x8*)(XCB + (tb * 16 + fr) * 272 + (ks * 32 + fq * 8) * 2);
;                 ar = __builtin_amdgcn_mfma_f32_16x16x32_bf16(a, wf[0][ks], ar, 0, 0, 0);
;                 ai = __builtin_amdgcn_mfma_f32_16x16x32_bf16(a, wf[1][ks], ai, 0, 0, 0);
;             }
; #pragma unroll
;             for (int j = 0; j < 4; ++j) {
;                 const int token = fq * 16 + tb * 4 + j;
;                 const float xcv = XCF[token * 132 + chl];
;                 const float e1 = __expf(fminf(-(ar[j] + brv), 40.f)), e2 = __expf(fminf(-(ai[j] + biv), 40.f));
;                 const float inv = __builtin_amdgcn_rcpf((1.0f + e1) * (1.0f + e2));
;                 const float r = inv * (1.0f + e2), ig = inv * (1.0f + e1);
;                 const float a = __expf(clv * r);
;                 const float bb = __builtin_amdgcn_sqrtf(fmaxf(1.0f - a * a, 0.f)) * (ig * xcv);
;                 hrun = a * hrun + bb; prun *= a;
;                 if (PASSB) { hl[tb * 4 + j] = hrun; pl[tb * 4 + j] = prun; }
;             }
;         }
;         const float P0 = __shfl(prun, fr), H0 = __shfl(hrun, fr), P1 = __shfl(prun, fr + 16), H1 = __shfl(hrun, fr + 16);
;         const float P2 = __shfl(prun, fr + 32), H2 = __shfl(hrun, fr + 32), P3 = __shfl(prun, fr + 48), H3 = __shfl(hrun, fr + 48);
;         const float s0 = P0 * Cst + H0, s1 = P1 * s0 + H1, s2 = P2 * s1 + H2, s3 = P3 * s2 + H3;
;         const float cin = fq == 0 ? Cst : (fq == 1 ? s0 : (fq == 2 ? s1 : s2));
;         Cst = s3;
;         if (PASSB) {
; #pragma unroll
;             for (int q = 0; q < 16; ++q) {
;                 const float hv = hl[q] + pl[q] * cin;
;                 const float gt = __uint_as_float(((unsigned)gvv[q]) << 16);
;                 YA[obase + (size_t)q * 1024] = (bf16_t)(cvt_pk_bf16(hv * gt, 0.f) & 0xffffu);
;             }
;         } else {
;             Pacc *= (P0 * P1) * (P2 * P3);
	v_mfma_f32_16x16x32_bf16 v[142:145], v[146:149], v[8:11], v[142:145]
	v_exp_f32_e32 v155, v132
	v_mfma_f32_16x16x32_bf16 v[132:135], v[146:149], v[12:15], v[134:137]
	v_fma_f32 v146, -v155, v155, 1.0 clamp
	v_sqrt_f32_e32 v146, v146
	s_waitcnt lgkmcnt(0)
	v_mfma_f32_16x16x32_bf16 v[142:145], v[138:141], v[0:3], v[142:145]
	v_rcp_f32_e32 v137, v156
	s_nop 0
	v_mul_f32_e32 v137, v151, v137
	v_mul_f32_e32 v136, v154, v153
	v_mfma_f32_16x16x32_bf16 v[132:135], v[138:141], v[4:7], v[132:135]
	s_nop 3
	v_fma_f32 v138, v142, s72, v200
	s_nop 2
	v_fma_f32 v132, v132, s72, v201
	v_min_f32_e32 v132, s73, v132
	v_exp_f32_e32 v138, v138
	v_exp_f32_e32 v139, v132
	v_mul_f32_e32 v132, v155, v152
	v_fmac_f32_e32 v132, v137, v146
	v_add_f32_e32 v138, 1.0, v138
	v_add_f32_e32 v139, 1.0, v139
	v_rcp_f32_e32 v140, v139
	v_fma_f32 v133, v133, s72, v201
	v_min_f32_e32 v133, s73, v133
	v_rcp_f32_e32 v139, v138
	s_nop 0
	v_mul_f32_e32 v138, v202, v139
	v_fma_f32 v139, v143, s72, v200
	v_min_f32_e32 v139, s73, v139
	v_exp_f32_e32 v139, v139
	v_exp_f32_e32 v133, v133
	v_mul_f32_e32 v142, v155, v136
	v_add_u32_e32 v136, 0x5c00, v131
	v_add_f32_e32 v143, 1.0, v139
	v_add_f32_e32 v146, 1.0, v133
	ds_read2_b32 v[136:137], v136 offset0:48 offset1:180
	v_exp_f32_e32 v138, v138
	s_waitcnt lgkmcnt(0)
	v_mul_f32_e32 v133, v136, v140
	v_fma_f32 v134, v134, s72, v201
	v_rcp_f32_e32 v140, v143
	v_fma_f32 v141, -v138, v138, 1.0 clamp
	v_mul_f32_e32 v140, v202, v140
	v_sqrt_f32_e32 v139, v141
	v_exp_f32_e32 v141, v140
	v_mul_f32_e32 v136, v132, v138
	v_min_f32_e32 v134, s73, v134
	v_pk_fma_f32 v[132:133], v[132:133], v[138:139], v[136:137] op_sel_hi:[1,1,0]
	v_mul_f32_e32 v136, v142, v138
	v_fma_f32 v138, -v141, v141, 1.0 clamp
	v_sqrt_f32_e32 v140, v138
	v_fma_f32 v138, v144, s72, v200
	v_min_f32_e32 v138, s73, v138
	v_exp_f32_e32 v138, v138
	v_exp_f32_e32 v139, v134
	v_rcp_f32_e32 v132, v146
	s_nop 0
	v_mul_f32_e32 v132, v137, v132
	v_add_f32_e32 v142, 1.0, v138
	v_add_f32_e32 v137, 1.0, v139
	v_mul_f32_e32 v138, v142, v137
	v_rcp_f32_e32 v143, v138
	v_mul_f32_e32 v134, v132, v140
	v_pk_fma_f32 v[132:133], v[132:133], v[140:141], v[134:135] op_sel_hi:[1,1,0]
	v_add_u32_e32 v131, 0x6000, v131
	v_mul_f32_e32 v132, v137, v143
	v_mul_f32_e32 v132, v202, v132
	v_exp_f32_e32 v137, v132
	v_fma_f32 v132, v145, s72, v200
	v_min_f32_e32 v132, s73, v132
	v_exp_f32_e32 v134, v132
	v_fma_f32 v132, v135, s72, v201
	v_min_f32_e32 v132, s73, v132
	v_exp_f32_e32 v135, v132
	v_mul_f32_e32 v140, v141, v136
	ds_read2_b32 v[138:139], v131 offset0:56 offset1:188
	v_mul_f32_e32 v131, v142, v143
	v_pk_add_f32 v[134:135], v[134:135], 1.0 op_sel_hi:[1,0]
	v_fma_f32 v132, -v137, v137, 1.0 clamp
	v_sqrt_f32_e32 v136, v132
	s_waitcnt lgkmcnt(0)
	v_mul_f32_e32 v132, v138, v131
	v_rcp_f32_e32 v131, v134
	s_nop 0
	v_mul_f32_e32 v131, v202, v131
	v_exp_f32_e32 v141, v131
	v_mul_f32_e32 v138, v132, v136
	v_pk_fma_f32 v[132:133], v[132:133], v[136:137], v[138:139] op_sel_hi:[1,1,0]
	v_mul_f32_e32 v131, v137, v140
	v_fma_f32 v132, -v141, v141, 1.0 clamp
	v_sqrt_f32_e32 v140, v132
	v_rcp_f32_e32 v132, v135
	s_nop 0
	v_mul_f32_e32 v132, v139, v132
	v_mul_f32_e32 v134, v133, v141
	v_pk_fma_f32 v[132:133], v[132:133], v[140:141], v[134:135] op_sel_hi:[1,1,0]
	v_mul_f32_e32 v131, v141, v131
	ds_bpermute_b32 v134, v119, v131
	ds_bpermute_b32 v133, v119, v132
	ds_bpermute_b32 v136, v119, v131 offset:64
	ds_bpermute_b32 v138, v119, v132 offset:64
	ds_bpermute_b32 v135, v119, v131 offset:128
	ds_bpermute_b32 v139, v119, v132 offset:128
	ds_bpermute_b32 v132, v119, v132 offset:192
	ds_bpermute_b32 v137, v119, v131 offset:192
	s_waitcnt lgkmcnt(6)
	v_fmac_f32_e32 v133, v113, v134
	s_waitcnt lgkmcnt(4)
	v_fmac_f32_e32 v138, v133, v136
	s_waitcnt lgkmcnt(2)
	v_fmac_f32_e32 v139, v138, v135
	s_waitcnt lgkmcnt(1)
	v_mov_b32_e32 v113, v132
	s_waitcnt lgkmcnt(0)
	v_pk_mul_f32 v[132:133], v[134:135], v[136:137]
	v_fmac_f32_e32 v113, v139, v137
	v_mul_f32_e32 v131, v132, v133
	v_mul_f32_e32 v108, v108, v131
	s_cbranch_scc1 .LBB0_510

; #define LAS __attribute__((address_space(3)))
; template <bool PASSB>
; __device__ __forceinline__ void lru_unit(LAS unsigned char* lds, const Params& p, int b, int hd, int chunk) {
;     ...
;         for (int tb = 0; tb < 4; ++tb) {
;             f32x4 ar = (f32x4){0.f, 0.f, 0.f, 0.f}, ai = (f32x4){0.f, 0.f, 0.f, 0.f};
; #pragma unroll
;             for (int ks = 0; ks < 4; ++ks) {
;                 const bf16x8 a = *(const LAS bf16x8*)(XCB + (tb * 16 + fr) * 272 + (ks * 32 + fq * 8) * 2);
;                 ar = __builtin_amdgcn_mfma_f32_16x16x32_bf16(a, wf[0][ks], ar, 0, 0, 0);
;                 ai = __builtin_amdgcn_mfma_f32_16x16x32_bf16(a, wf[1][ks], ai, 0, 0, 0);
;             }
; #pragma unroll
;             for (int j = 0; j < 4; ++j) {
;                 const int token = fq * 16 + tb * 4 + j;
;                 const float xcv = XCF[token * 132 + chl];
;                 const float e1 = __expf(fminf(-(ar[j] + brv), 40.f)), e2 = __expf(fminf(-(ai[j] + biv), 40.f));
;                 const float inv = __builtin_amdgcn_rcpf((1.0f + e1) * (1.0f + e2));
;                 const float r = inv * (1.0f + e2), ig = inv * (1.0f + e1);
;                 const float a = __expf(clv * r);
;                 const float bb = __builtin_amdgcn_sqrtf(fmaxf(1.0f - a * a, 0.f)) * (ig * xcv);
;                 hrun = a * hrun + bb; prun *= a;
;                 if (PASSB) { hl[tb * 4 + j] = hrun; pl[tb * 4 + j] = prun; }
;             }
.LBB0_601:
.LBB0_603:
.LBB0_605:
.LBB0_607:
.LBB0_609:
.LBB0_611:
.LBB0_613:
.LBB0_615:
	v_add3_u32 v145, s12, v116, v130
	ds_read_b128 v[104:107], v145
	ds_read_b128 v[108:111], v145 offset:64
	ds_read_b128 v[146:149], v145 offset:128
	ds_read_b128 v[150:153], v145 offset:192
	v_lshlrev_b32_e32 v112, 2, v114
	s_waitcnt lgkmcnt(3)
	v_mfma_f32_16x16x32_bf16 v[140:143], v[104:107], v[24:27], 0
	v_mfma_f32_16x16x32_bf16 v[104:107], v[104:107], v[28:31], 0
	s_waitcnt lgkmcnt(2)
	v_mfma_f32_16x16x32_bf16 v[140:143], v[108:111], v[16:19], v[140:143]
	v_mfma_f32_16x16x32_bf16 v[104:107], v[108:111], v[20:23], v[104:107]
	s_waitcnt lgkmcnt(1)
	v_mfma_f32_16x16x32_bf16 v[108:111], v[146:149], v[8:11], v[140:143]
	v_mfma_f32_16x16x32_bf16 v[104:107], v[146:149], v[12:15], v[104:107]
	s_nop 3
	v_add3_u32 v143, s12, v112, v121
	v_add_u32_e32 v127, 0x4400, v143
	s_waitcnt lgkmcnt(0)
	v_mfma_f32_16x16x32_bf16 v[108:111], v[150:153], v[0:3], v[108:111]
	v_mfma_f32_16x16x32_bf16 v[104:107], v[150:153], v[4:7], v[104:107]
	s_nop 6
	v_fma_f32 v108, v108, s72, v200
	v_fma_f32 v104, v104, s72, v201
	v_min_f32_e32 v104, s73, v104
	v_exp_f32_e32 v108, v108
	v_exp_f32_e32 v104, v104
	v_fma_f32 v105, v105, s72, v201
	v_min_f32_e32 v105, s73, v105
	v_add_f32_e32 v108, 1.0, v108
	v_add_f32_e32 v129, 1.0, v104
	v_fma_f32 v109, v109, s72, v200
	v_exp_f32_e32 v128, v105
	ds_read2_b32 v[104:105], v127 offset1:132
	v_rcp_f32_e32 v127, v108
	s_nop 0
	v_mul_f32_e32 v127, v202, v127
	v_exp_f32_e32 v109, v109
	v_exp_f32_e32 v127, v127
	v_add_f32_e32 v128, 1.0, v128
	v_rcp_f32_e32 v108, v129
	v_add_f32_e32 v109, 1.0, v109
	v_fma_f32 v140, -v127, v127, 1.0 clamp
	v_fma_f32 v110, v110, s72, v200
	v_fma_f32 v106, v106, s72, v201
	v_min_f32_e32 v110, s73, v110
	v_sqrt_f32_e32 v140, v140
	v_exp_f32_e32 v110, v110
	v_exp_f32_e32 v106, v106
	s_waitcnt lgkmcnt(0)
	v_mul_f32_e32 v104, v104, v108
	v_rcp_f32_e32 v108, v109
	v_mul_f32_e32 v140, v104, v140
	v_rcp_f32_e32 v104, v128
	v_mul_f32_e32 v108, v202, v108
	v_mul_f32_e32 v104, v105, v104
	v_add_f32_e32 v105, 1.0, v110
	v_add_f32_e32 v106, 1.0, v106
	v_exp_f32_e32 v108, v108
	v_rcp_f32_e32 v144, v106
	v_fmac_f32_e32 v140, 0, v127
	v_fma_f32 v109, -v108, v108, 1.0 clamp
	v_rcp_f32_e32 v106, v105
	s_nop 0
	v_mul_f32_e32 v106, v202, v106
	v_sqrt_f32_e32 v109, v109
	v_exp_f32_e32 v158, v106
	v_mul_f32_e32 v141, v108, v140
	v_fmac_f32_e32 v141, v104, v109
	v_add_u32_e32 v104, 0x4800, v143
	ds_read2_b32 v[128:129], v104 offset0:8 offset1:140
	ds_read_b128 v[146:149], v145 offset:4352
	v_fma_f32 v104, -v158, v158, 1.0 clamp
	v_sqrt_f32_e32 v159, v104
	v_fma_f32 v104, v111, s72, v200
	v_min_f32_e32 v104, s73, v104
	v_mul_f32_e32 v142, v127, v108
	ds_read_b128 v[108:111], v145 offset:4416
	v_exp_f32_e32 v154, v104
	v_fma_f32 v104, v107, s72, v201
	v_min_f32_e32 v155, s73, v104
	s_waitcnt lgkmcnt(1)
	v_mfma_f32_16x16x32_bf16 v[150:153], v[146:149], v[24:27], 0
	v_add_f32_e32 v160, 1.0, v154
	v_mul_f32_e32 v128, v128, v144
	v_mul_f32_e32 v144, v158, v141
	v_mfma_f32_16x16x32_bf16 v[104:107], v[146:149], v[28:31], 0
	v_exp_f32_e32 v155, v155
	ds_read_b128 v[146:149], v145 offset:4480
	s_waitcnt lgkmcnt(1)
	v_mfma_f32_16x16x32_bf16 v[150:153], v[108:111], v[16:19], v[150:153]
	v_fmac_f32_e32 v144, v128, v159
	v_add_f32_e32 v161, 1.0, v155
	ds_read_b128 v[154:157], v145 offset:4544
	v_mfma_f32_16x16x32_bf16 v[104:107], v[108:111], v[20:23], v[104:107]
	s_waitcnt lgkmcnt(1)
	v_mfma_f32_16x16x32_bf16 v[108:111], v[146:149], v[8:11], v[150:153]
	v_rcp_f32_e32 v128, v160
	s_nop 0
	v_mul_f32_e32 v128, v202, v128
	v_mfma_f32_16x16x32_bf16 v[104:107], v[146:149], v[12:15], v[104:107]
	v_exp_f32_e32 v128, v128
	v_rcp_f32_e32 v147, v161
	s_waitcnt lgkmcnt(0)
	v_mfma_f32_16x16x32_bf16 v[108:111], v[154:157], v[0:3], v[108:111]
	v_mul_f32_e32 v146, v158, v142
	v_fma_f32 v148, -v128, v128, 1.0 clamp
	v_mfma_f32_16x16x32_bf16 v[104:107], v[154:157], v[4:7], v[104:107]
	v_sqrt_f32_e32 v148, v148
	s_nop 2
	s_nop 0
	v_fma_f32 v108, v108, s72, v200
	v_exp_f32_e32 v108, v108
	s_nop 0
	v_fma_f32 v104, v104, s72, v201
	v_exp_f32_e32 v104, v104
	v_add_f32_e32 v108, 1.0, v108
	v_fma_f32 v109, v109, s72, v200
	v_fma_f32 v105, v105, s72, v201
	v_add_f32_e32 v104, 1.0, v104
	v_rcp_f32_e32 v149, v108
	v_min_f32_e32 v109, s73, v109
	v_min_f32_e32 v105, s73, v105
	v_rcp_f32_e32 v108, v104
	v_mul_f32_e32 v104, v202, v149
	v_exp_f32_e32 v104, v104
	v_exp_f32_e32 v109, v109
	v_exp_f32_e32 v105, v105
	v_mul_f32_e32 v129, v129, v147
	v_mul_f32_e32 v147, v128, v144
	v_fmac_f32_e32 v147, v129, v148
	v_mul_f32_e32 v148, v128, v146
	v_add_u32_e32 v128, 0x4c00, v143
	ds_read2_b32 v[128:129], v128 offset0:16 offset1:148
	v_fma_f32 v150, -v104, v104, 1.0 clamp
	v_add_f32_e32 v109, 1.0, v109
	v_add_f32_e32 v105, 1.0, v105
	v_sqrt_f32_e32 v150, v150
	v_mul_f32_e32 v151, v109, v105
	v_rcp_f32_e32 v151, v151
	s_waitcnt lgkmcnt(0)
	v_mul_f32_e32 v108, v128, v108
	v_mul_f32_e32 v149, v108, v150
	v_fmac_f32_e32 v149, v147, v104
	v_mul_f32_e32 v150, v148, v104
	v_mul_f32_e32 v104, v109, v151
	v_fma_f32 v109, v110, s72, v200
	v_fma_f32 v106, v106, s72, v201
	v_exp_f32_e32 v109, v109
	v_exp_f32_e32 v106, v106
	v_mul_f32_e32 v105, v105, v151
	v_mul_f32_e32 v105, v202, v105
	v_add_f32_e32 v109, 1.0, v109
	v_add_f32_e32 v106, 1.0, v106
	v_exp_f32_e32 v105, v105
	v_mul_f32_e32 v104, v129, v104
	v_fma_f32 v108, -v105, v105, 1.0 clamp
	v_mul_f32_e32 v151, v105, v149
	v_mul_f32_e32 v152, v105, v150
	v_rcp_f32_e32 v105, v109
	s_nop 0
	v_mul_f32_e32 v105, v202, v105
	v_sqrt_f32_e32 v108, v108
	v_exp_f32_e32 v153, v105
	v_rcp_f32_e32 v162, v106
	v_fmac_f32_e32 v151, v104, v108
	v_add_u32_e32 v104, 0x5000, v143
	ds_read2_b32 v[128:129], v104 offset0:24 offset1:156
	ds_read_b128 v[154:157], v145 offset:8704
	v_fma_f32 v104, -v153, v153, 1.0 clamp
	v_sqrt_f32_e32 v166, v104
	v_fma_f32 v104, v111, s72, v200
	v_min_f32_e32 v104, s73, v104
	ds_read_b128 v[108:111], v145 offset:8768
	v_exp_f32_e32 v163, v104
	v_fma_f32 v104, v107, s72, v201
	v_min_f32_e32 v164, s73, v104
	s_waitcnt lgkmcnt(1)
; #define LAS __attribute__((address_space(3)))
; template <bool PASSB>
; __device__ __forceinline__ void lru_unit(LAS unsigned char* lds, const Params& p, int b, int hd, int chunk) {
;     ...
;         for (int tb = 0; tb < 4; ++tb) {
;             f32x4 ar = (f32x4){0.f, 0.f, 0.f, 0.f}, ai = (f32x4){0.f, 0.f, 0.f, 0.f};
; #pragma unroll
;             for (int ks = 0; ks < 4; ++ks) {
;                 const bf16x8 a = *(const LAS bf16x8*)(XCB + (tb * 16 + fr) * 272 + (ks * 32 + fq * 8) * 2);
;                 ar = __builtin_amdgcn_mfma_f32_16x16x32_bf16(a, wf[0][ks], ar, 0, 0, 0);
;                 ai = __builtin_amdgcn_mfma_f32_16x16x32_bf16(a, wf[1][ks], ai, 0, 0, 0);
;             }
; #pragma unroll
;             for (int j = 0; j < 4; ++j) {
;                 const int token = fq * 16 + tb * 4 + j;
;                 const float xcv = XCF[token * 132 + chl];
;                 const float e1 = __expf(fminf(-(ar[j] + brv), 40.f)), e2 = __expf(fminf(-(ai[j] + biv), 40.f));
;                 const float inv = __builtin_amdgcn_rcpf((1.0f + e1) * (1.0f + e2));
;                 const float r = inv * (1.0f + e2), ig = inv * (1.0f + e1);
;                 const float a = __expf(clv * r);
;                 const float bb = __builtin_amdgcn_sqrtf(fmaxf(1.0f - a * a, 0.f)) * (ig * xcv);
;                 hrun = a * hrun + bb; prun *= a;
;                 if (PASSB) { hl[tb * 4 + j] = hrun; pl[tb * 4 + j] = prun; }
;             }
	v_mfma_f32_16x16x32_bf16 v[158:161], v[154:157], v[24:27], 0
	v_mul_f32_e32 v167, v128, v162
	v_add_f32_e32 v168, 1.0, v163
	v_mul_f32_e32 v128, v153, v151
	v_mfma_f32_16x16x32_bf16 v[104:107], v[154:157], v[28:31], 0
	v_exp_f32_e32 v164, v164
	ds_read_b128 v[154:157], v145 offset:8832
	s_waitcnt lgkmcnt(1)
	v_mfma_f32_16x16x32_bf16 v[158:161], v[108:111], v[16:19], v[158:161]
	v_fmac_f32_e32 v128, v167, v166
	v_add_f32_e32 v169, 1.0, v164
	ds_read_b128 v[162:165], v145 offset:8896
	v_mfma_f32_16x16x32_bf16 v[104:107], v[108:111], v[20:23], v[104:107]
	v_mul_f32_e32 v153, v153, v152
	s_waitcnt lgkmcnt(1)
	v_mfma_f32_16x16x32_bf16 v[108:111], v[154:157], v[8:11], v[158:161]
	v_mfma_f32_16x16x32_bf16 v[104:107], v[154:157], v[12:15], v[104:107]
	s_nop 1
	v_rcp_f32_e32 v158, v168
	s_nop 0
	v_mul_f32_e32 v154, v202, v158
	s_waitcnt lgkmcnt(0)
	v_mfma_f32_16x16x32_bf16 v[108:111], v[162:165], v[0:3], v[108:111]
	v_exp_f32_e32 v154, v154
	v_rcp_f32_e32 v155, v169
	s_nop 0
	v_mul_f32_e32 v155, v129, v155
	v_mfma_f32_16x16x32_bf16 v[104:107], v[162:165], v[4:7], v[104:107]
	v_fma_f32 v156, -v154, v154, 1.0 clamp
	s_nop 2
	v_fma_f32 v108, v108, s72, v200
	v_exp_f32_e32 v108, v108
	s_nop 0
	s_nop 0
	v_fma_f32 v104, v104, s72, v201
	v_exp_f32_e32 v104, v104
	v_add_f32_e32 v108, 1.0, v108
	v_fma_f32 v109, v109, s72, v200
	v_fma_f32 v105, v105, s72, v201
	v_add_f32_e32 v104, 1.0, v104
	v_rcp_f32_e32 v158, v108
	v_min_f32_e32 v109, s73, v109
	v_min_f32_e32 v105, s73, v105
	v_rcp_f32_e32 v108, v104
	v_exp_f32_e32 v109, v109
	v_exp_f32_e32 v105, v105
	v_sqrt_f32_e32 v156, v156
	v_mul_f32_e32 v104, v202, v158
	v_exp_f32_e32 v104, v104
	v_mul_f32_e32 v129, v154, v128
	v_add_f32_e32 v159, 1.0, v109
	v_add_f32_e32 v105, 1.0, v105
	v_fmac_f32_e32 v129, v155, v156
	v_add_u32_e32 v155, 0x5400, v143
	v_mul_f32_e32 v109, v159, v105
	ds_read2_b32 v[156:157], v155 offset0:32 offset1:164
	v_rcp_f32_e32 v160, v109
	v_fma_f32 v155, -v104, v104, 1.0 clamp
	v_fma_f32 v110, v110, s72, v200
	v_fma_f32 v106, v106, s72, v201
	v_sqrt_f32_e32 v155, v155
	v_min_f32_e32 v110, s73, v110
	v_min_f32_e32 v106, s73, v106
	v_mul_f32_e32 v105, v105, v160
	s_waitcnt lgkmcnt(0)
	v_mul_f32_e32 v108, v156, v108
	v_mul_f32_e32 v105, v202, v105
	v_exp_f32_e32 v156, v110
	v_exp_f32_e32 v106, v106
	v_mul_f32_e32 v154, v154, v153
	v_mul_f32_e32 v109, v108, v155
	v_exp_f32_e32 v105, v105
	v_fmac_f32_e32 v109, v129, v104
	v_mul_f32_e32 v155, v154, v104
	v_mul_f32_e32 v104, v159, v160
	v_mul_f32_e32 v104, v157, v104
	v_add_f32_e32 v157, 1.0, v156
	v_add_f32_e32 v106, 1.0, v106
	v_mul_f32_e32 v156, v157, v106
	v_fma_f32 v108, -v105, v105, 1.0 clamp
	v_rcp_f32_e32 v162, v156
	v_sqrt_f32_e32 v108, v108
	v_mul_f32_e32 v110, v105, v109
	v_mul_f32_e32 v156, v105, v155
	v_mul_f32_e32 v105, v106, v162
	v_mul_f32_e32 v105, v202, v105
	v_fmac_f32_e32 v110, v104, v108
	v_add_u32_e32 v104, 0x5800, v143
	v_exp_f32_e32 v106, v105
	ds_read2_b32 v[104:105], v104 offset0:40 offset1:172
	ds_read_b128 v[158:161], v145 offset:13056
	v_mul_f32_e32 v108, v157, v162
	ds_read_b128 v[162:165], v145 offset:13120
	ds_read_b128 v[172:175], v145 offset:13184
	s_waitcnt lgkmcnt(2)
	v_mfma_f32_16x16x32_bf16 v[166:169], v[158:161], v[24:27], 0
	v_fma_f32 v111, v111, s72, v200
	v_fma_f32 v107, v107, s72, v201
	v_min_f32_e32 v111, s73, v111
	v_mfma_f32_16x16x32_bf16 v[158:161], v[158:161], v[28:31], 0
	s_waitcnt lgkmcnt(1)
	v_mfma_f32_16x16x32_bf16 v[166:169], v[162:165], v[16:19], v[166:169]
	v_exp_f32_e32 v111, v111
	v_exp_f32_e32 v107, v107
	v_fma_f32 v157, -v106, v106, 1.0 clamp
	v_mfma_f32_16x16x32_bf16 v[158:161], v[162:165], v[20:23], v[158:161]
	ds_read_b128 v[162:165], v145 offset:13248
	v_mul_f32_e32 v104, v104, v108
	v_add_f32_e32 v108, 1.0, v111
	s_waitcnt lgkmcnt(1)
	v_mfma_f32_16x16x32_bf16 v[166:169], v[172:175], v[8:11], v[166:169]
	v_add_f32_e32 v107, 1.0, v107
	v_mfma_f32_16x16x32_bf16 v[158:161], v[172:175], v[12:15], v[158:161]
	v_sqrt_f32_e32 v157, v157
	v_mul_f32_e32 v111, v106, v110
	s_waitcnt lgkmcnt(0)
; template <bool PASSB>
; __device__ __forceinline__ void lru_unit(LAS unsigned char* lds, const Params& p, int b, int hd, int chunk) {
;     ...
;             for (int j = 0; j < 4; ++j) {
;                 const int token = fq * 16 + tb * 4 + j;
;                 const float xcv = XCF[token * 132 + chl];
;                 const float e1 = __expf(fminf(-(ar[j] + brv), 40.f)), e2 = __expf(fminf(-(ai[j] + biv), 40.f));
;                 const float inv = __builtin_amdgcn_rcpf((1.0f + e1) * (1.0f + e2));
;                 const float r = inv * (1.0f + e2), ig = inv * (1.0f + e1);
;                 const float a = __expf(clv * r);
;                 const float bb = __builtin_amdgcn_sqrtf(fmaxf(1.0f - a * a, 0.f)) * (ig * xcv);
;                 hrun = a * hrun + bb; prun *= a;
;                 if (PASSB) { hl[tb * 4 + j] = hrun; pl[tb * 4 + j] = prun; }
;             }
;         }
;         const float P0 = __shfl(prun, fr), H0 = __shfl(hrun, fr), P1 = __shfl(prun, fr + 16), H1 = __shfl(hrun, fr + 16);
;         const float P2 = __shfl(prun, fr + 32), H2 = __shfl(hrun, fr + 32), P3 = __shfl(prun, fr + 48), H3 = __shfl(hrun, fr + 48);
;         const float s0 = P0 * Cst + H0, s1 = P1 * s0 + H1, s2 = P2 * s1 + H2, s3 = P3 * s2 + H3;
;         const float cin = fq == 0 ? Cst : (fq == 1 ? s0 : (fq == 2 ? s1 : s2));
	v_mfma_f32_16x16x32_bf16 v[166:169], v[162:165], v[0:3], v[166:169]
	v_fmac_f32_e32 v111, v104, v157
	v_rcp_f32_e32 v104, v108
	v_mul_f32_e32 v145, v106, v156
	v_mfma_f32_16x16x32_bf16 v[160:163], v[162:165], v[4:7], v[158:161]
	v_rcp_f32_e32 v106, v107
	s_nop 2
	v_fma_f32 v108, v166, s72, v200
	v_mul_f32_e32 v104, v202, v104
	v_min_f32_e32 v108, s73, v108
	s_nop 0
	v_fma_f32 v157, v160, s72, v201
	v_min_f32_e32 v157, s73, v157
	v_exp_f32_e32 v104, v104
	v_exp_f32_e32 v108, v108
	v_exp_f32_e32 v157, v157
	v_mul_f32_e32 v105, v105, v106
	v_fma_f32 v107, -v104, v104, 1.0 clamp
	v_add_f32_e32 v108, 1.0, v108
	v_add_f32_e32 v158, 1.0, v157
	v_mul_f32_e32 v157, v108, v158
	v_sqrt_f32_e32 v107, v107
	v_rcp_f32_e32 v159, v157
	v_mul_f32_e32 v157, v104, v111
	v_fma_f32 v160, v167, s72, v200
	v_fmac_f32_e32 v157, v105, v107
	v_mul_f32_e32 v105, v158, v159
	v_fma_f32 v161, v161, s72, v201
	v_mul_f32_e32 v105, v202, v105
	v_min_f32_e32 v160, s73, v160
	v_min_f32_e32 v161, s73, v161
	v_exp_f32_e32 v106, v105
	v_exp_f32_e32 v160, v160
	v_exp_f32_e32 v161, v161
	v_mul_f32_e32 v158, v104, v145
	v_add_u32_e32 v104, 0x5c00, v143
	ds_read2_b32 v[104:105], v104 offset0:48 offset1:180
	v_fma_f32 v107, -v106, v106, 1.0 clamp
	v_add_f32_e32 v164, 1.0, v160
	v_add_f32_e32 v160, 1.0, v161
	v_mul_f32_e32 v161, v164, v160
	v_sqrt_f32_e32 v107, v107
	v_rcp_f32_e32 v161, v161
	v_mul_f32_e32 v108, v108, v159
	s_waitcnt lgkmcnt(0)
	v_mul_f32_e32 v104, v104, v108
	v_mul_f32_e32 v159, v104, v107
	v_mul_f32_e32 v104, v160, v161
	v_mul_f32_e32 v104, v202, v104
	v_exp_f32_e32 v104, v104
	v_fmac_f32_e32 v159, v157, v106
	v_mul_f32_e32 v160, v158, v106
	v_mul_f32_e32 v106, v164, v161
	v_mul_f32_e32 v105, v105, v106
	v_fma_f32 v106, v168, s72, v200
	v_fma_f32 v108, v162, s72, v201
	v_fma_f32 v107, -v104, v104, 1.0 clamp
	v_min_f32_e32 v108, s73, v108
	v_sqrt_f32_e32 v107, v107
	v_exp_f32_e32 v106, v106
	v_exp_f32_e32 v108, v108
	v_mul_f32_e32 v161, v104, v159
	v_mul_f32_e32 v162, v104, v160
	v_add_u32_e32 v104, 0x6000, v143
	v_fma_f32 v143, v169, s72, v200
	v_fma_f32 v163, v163, s72, v201
	v_fmac_f32_e32 v161, v105, v107
	v_add_f32_e32 v106, 1.0, v106
	v_add_f32_e32 v107, 1.0, v108
	v_min_f32_e32 v143, s73, v143
	v_min_f32_e32 v163, s73, v163
	v_rcp_f32_e32 v108, v106
	v_exp_f32_e32 v143, v143
	v_exp_f32_e32 v163, v163
	ds_read2_b32 v[104:105], v104 offset0:56 offset1:188
	v_rcp_f32_e32 v106, v107
	v_add_f32_e32 v164, 1.0, v143
	v_add_f32_e32 v143, 1.0, v163
	v_mul_f32_e32 v107, v202, v108
	v_mul_f32_e32 v163, v164, v143
	v_rcp_f32_e32 v165, v163
	v_exp_f32_e32 v107, v107
	s_waitcnt lgkmcnt(0)
	v_mul_f32_e32 v104, v104, v106
	v_mul_f32_e32 v106, v143, v165
	v_fma_f32 v108, -v107, v107, 1.0 clamp
	v_mul_f32_e32 v106, v202, v106
	v_sqrt_f32_e32 v108, v108
	v_exp_f32_e32 v106, v106
	v_mul_f32_e32 v143, v107, v161
	v_mul_f32_e32 v163, v107, v162
	v_fmac_f32_e32 v143, v104, v108
	v_fma_f32 v104, -v106, v106, 1.0 clamp
	v_sqrt_f32_e32 v104, v104
	v_mul_f32_e32 v107, v164, v165
	v_mul_f32_e32 v105, v105, v107
	v_mul_f32_e32 v164, v106, v143
	v_fmac_f32_e32 v164, v105, v104
	v_lshl_add_u64 v[104:105], v[124:125], 0, s[8:9]
	v_mul_f32_e32 v165, v106, v163
	ds_bpermute_b32 v185, v117, v165
	ds_bpermute_b32 v176, v117, v164
	ds_bpermute_b32 v187, v117, v165 offset:64
	ds_bpermute_b32 v182, v117, v164 offset:64
	ds_bpermute_b32 v188, v117, v165 offset:128
	ds_bpermute_b32 v174, v117, v164 offset:128
	ds_bpermute_b32 v175, v117, v165 offset:192
	ds_bpermute_b32 v106, v117, v164 offset:192
	s_waitcnt lgkmcnt(6)
	v_fmac_f32_e32 v176, v137, v185
	s_waitcnt lgkmcnt(4)
	v_fmac_f32_e32 v182, v176, v187
	v_or_b32_e32 v108, 64, v117
	v_or_b32_e32 v107, 0x80, v117
	s_waitcnt lgkmcnt(2)
	v_fmac_f32_e32 v174, v182, v188
	v_cmp_lt_i32_e32 vcc, 0, v135
	s_and_saveexec_b64 s[10:11], vcc
	s_cbranch_execz .LBB0_621
	v_cmp_ne_u32_e32 vcc, 1, v135
	s_and_saveexec_b64 s[12:13], vcc
	s_xor_b64 s[12:13], exec, s[12:13]
	v_cndmask_b32_e64 v137, v174, v182, s[0:1]
	s_andn2_saveexec_b64 s[12:13], s[12:13]
	v_mov_b32_e32 v137, v176
	s_or_b64 exec, exec, s[12:13]
